# seams 1,6,8: own-group barrier only; the neighbour-group WAR check is deferred to just before each workgroup's first overlay store of the next phase
# speedup vs baseline: 1.0060x; 1.0060x over previous
_Z14fwd_megakernel4Args:
	s_mov_b32 s99, 0
	s_load_dwordx8 s[36:43], s[0:1], 0x80
	s_load_dword s3, s[0:1], 0xa8
	s_load_dwordx2 s[14:15], s[0:1], 0xa0
	s_add_u32 s6, s0, 0xa0
	v_and_b32_e32 v241, 0x3ff, v0
	s_addc_u32 s7, s1, 0
	v_cmp_gt_u32_e32 vcc, 64, v241
	s_and_saveexec_b64 s[4:5], vcc
	v_lshl_add_u32 v1, v241, 2, 0
	v_add_u32_e32 v1, 0x20000, v1
	v_mov_b32_e32 v2, 0
	ds_write_b32 v1, v2
	s_or_b64 exec, exec, s[4:5]
	s_waitcnt lgkmcnt(0)
	s_barrier
	s_add_u32 s34, s42, 0xe0000
	s_getreg_b32 s4, hwreg(HW_REG_XCC_ID, 0, 4)
	s_addc_u32 s35, s43, 0
	s_and_b32 s52, s4, 15
	v_cmp_eq_u32_e64 s[62:63], 0, v241
	s_and_saveexec_b64 s[4:5], s[62:63]
	s_cbranch_execz .LBB0_5
	s_mov_b64 s[8:9], exec
	v_mbcnt_lo_u32_b32 v1, s8, 0
	v_mbcnt_hi_u32_b32 v1, s9, v1
	v_cmp_eq_u32_e32 vcc, 0, v1
	s_and_b64 s[10:11], exec, vcc
	s_mov_b64 exec, s[10:11]
	s_cbranch_execz .LBB0_5
	s_lshl_b32 s10, s52, 8
	s_bcnt1_i32_b64 s8, s[8:9]
	v_mov_b32_e32 v1, s10
	v_mov_b32_e32 v2, s8
	global_atomic_add v1, v2, s[34:35] offset:1024
	s_and_b32 s12, s2, 7
	s_lshl_b32 s12, s12, 3
	s_add_u32 s12, s12, 0x3800
	s_add_i32 s13, s52, 1
	v_mov_b32_e32 v3, s12
	v_mov_b32_e32 v4, s13
	s_sub_i32 s13, 16, s52
	v_mov_b32_e32 v5, s13
	global_atomic_umax v3, v4, s[34:35]
	global_atomic_umax v3, v5, s[34:35] offset:4

.LBB0_232:
	s_cmp_eq_u32 s99, 0
	s_cbranch_scc1 .Lnochk232
	v_readlane_b32 s84, v0, 0
	v_readlane_b32 s14, v252, 45
	v_readlane_b32 s15, v252, 46
	s_mov_b64 exec, 1
	s_add_u32 s14, s14, 0xe3600
	s_addc_u32 s15, s15, 0
	s_lshr_b32 vcc_lo, s99, 16
	s_and_b32 s85, s99, 0xffff
	s_mov_b32 m0, 0
.Lchk232_next:
	s_ff1_i32_b32 vcc_hi, vcc_lo
	s_bitset0_b32 vcc_lo, vcc_hi
	s_lshl_b32 vcc_hi, vcc_hi, 6
.Lchk232_poll:
	v_mov_b32_e32 v0, vcc_hi
	s_nop 0
	global_load_dword v0, v0, s[14:15] sc1
	s_waitcnt vmcnt(0)
	v_readfirstlane_b32 s99, v0
	s_cmp_ge_u32 s99, s85
	s_cbranch_scc1 .Lchk232_ok
	s_sleep 1
	s_add_u32 m0, m0, 1
	s_cmp_lt_u32 m0, 0x4000
	s_cbranch_scc1 .Lchk232_poll
.Lchk232_ok:
	s_cmp_lg_u32 vcc_lo, 0
	s_cbranch_scc1 .Lchk232_next
	s_mov_b32 s99, 0
	s_mov_b64 exec, -1
	v_writelane_b32 v0, s84, 0
	s_nop 1

.LBB0_484:
	s_cmp_eq_u32 s99, 0
	s_cbranch_scc1 .Lnochk484
	v_readlane_b32 s48, v0, 0
	v_readlane_b32 s14, v252, 45
	v_readlane_b32 s15, v252, 46
	s_mov_b64 exec, 1
	s_add_u32 s14, s14, 0xe3600
	s_addc_u32 s15, s15, 0
	s_lshr_b32 vcc_lo, s99, 16
	s_and_b32 s49, s99, 0xffff
	s_mov_b32 m0, 0

.Lchk484_poll:
	v_mov_b32_e32 v0, vcc_hi
	s_nop 0
	global_load_dword v0, v0, s[14:15] sc1
	s_waitcnt vmcnt(0)
	v_readfirstlane_b32 s99, v0
	s_cmp_ge_u32 s99, s49
	s_cbranch_scc1 .Lchk484_ok
	s_sleep 1
	s_add_u32 m0, m0, 1
	s_cmp_lt_u32 m0, 0x4000
	s_cbranch_scc1 .Lchk484_poll
.Lchk484_ok:
	s_cmp_lg_u32 vcc_lo, 0
	s_cbranch_scc1 .Lchk484_next
	s_mov_b32 s99, 0
	s_mov_b64 exec, -1
	v_writelane_b32 v0, s48, 0
	s_nop 1

.Llb_tab:
	s_lshl_b32 s14, s8, 3
	s_lshr_b64 s[16:17], s[16:17], s14
	s_and_b32 s13, s16, 0xff
	s_lshl_b32 s14, 1, s8
	s_andn2_b32 s16, s13, s14
	s_mov_b32 s13, s14
	s_cmp_eq_u32 s16, 0
	s_cbranch_scc1 .Llb_have
	s_lshl_b32 s16, s16, 16
	s_or_b32 s99, s16, s9
